# hand-written expert-choice topk item: scalar popcount radix select (no ds_bpermute chain), prefix-sum slots, all returning tcount atomics issued back-to-back with one wait
# speedup vs baseline: 1.0456x; 1.0174x over previous
.LBB0_894:
	s_or_b64 exec, exec, s[0:1]
	s_cmp_lt_i32 s55, 32
	s_cselect_b64 s[0:1], -1, 0
	v_writelane_b32 v254, s0, 2
	s_cmp_gt_i32 s55, 31
	s_waitcnt lgkmcnt(0)
	v_writelane_b32 v254, s1, 3
	s_barrier
	s_cbranch_scc1 .LBB0_1129
	s_waitcnt vmcnt(0)
	v_readlane_b32 s0, v253, 4
	v_readlane_b32 s1, v253, 5
	v_lshrrev_b32_e32 v0, 6, v250
	s_sub_u32 s0, s0, 0x228
	s_subb_u32 s1, s1, 0
	s_load_dwordx4 s[76:79], s[0:1], 0x1a8
	s_load_dwordx2 s[80:81], s[0:1], 0x1b8
	s_load_dwordx4 s[84:87], s[0:1], 0x1d8
	v_readfirstlane_b32 s34, v0
	v_lshlrev_b32_e32 v3, 2, v0
	v_and_b32_e32 v4, 63, v250
	v_mov_b32_e32 v6, 1
	v_cmp_eq_u32_e64 s[30:31], 0, v4
	s_mov_b32 s33, s97
	s_waitcnt lgkmcnt(0)
.LtkA_item:
	s_lshr_b32 s2, s33, 4
	s_and_b32 s3, s33, 15
	v_lshl_add_u32 v1, s2, 12, v250
	s_lshl_b32 s6, s3, 2
	v_lshlrev_b32_e32 v2, 6, v1
	v_add_u32_e32 v2, s6, v2
	s_mov_b64 s[6:7], s[76:77]
	global_load_dword v16, v2, s[6:7]
	s_add_u32 s6, s6, 0x4000
	s_addc_u32 s7, s7, 0
	global_load_dword v17, v2, s[6:7]
	s_add_u32 s6, s6, 0x4000
	s_addc_u32 s7, s7, 0
	global_load_dword v18, v2, s[6:7]
	s_add_u32 s6, s6, 0x4000
	s_addc_u32 s7, s7, 0
	global_load_dword v19, v2, s[6:7]
	s_add_u32 s6, s6, 0x4000
	s_addc_u32 s7, s7, 0
	global_load_dword v20, v2, s[6:7]
	s_add_u32 s6, s6, 0x4000
	s_addc_u32 s7, s7, 0
	global_load_dword v21, v2, s[6:7]
	s_add_u32 s6, s6, 0x4000
	s_addc_u32 s7, s7, 0
	global_load_dword v22, v2, s[6:7]
	s_add_u32 s6, s6, 0x4000
	s_addc_u32 s7, s7, 0
	global_load_dword v23, v2, s[6:7]
	s_add_u32 s6, s6, 0x4000
	s_addc_u32 s7, s7, 0
	global_load_dword v24, v2, s[6:7]
	s_add_u32 s6, s6, 0x4000
	s_addc_u32 s7, s7, 0
	global_load_dword v25, v2, s[6:7]
	s_add_u32 s6, s6, 0x4000
	s_addc_u32 s7, s7, 0
	global_load_dword v26, v2, s[6:7]
	s_add_u32 s6, s6, 0x4000
	s_addc_u32 s7, s7, 0
	global_load_dword v27, v2, s[6:7]
	s_add_u32 s6, s6, 0x4000
	s_addc_u32 s7, s7, 0
	global_load_dword v28, v2, s[6:7]
	s_add_u32 s6, s6, 0x4000
	s_addc_u32 s7, s7, 0
	global_load_dword v29, v2, s[6:7]
	s_add_u32 s6, s6, 0x4000
	s_addc_u32 s7, s7, 0
	global_load_dword v30, v2, s[6:7]
	s_add_u32 s6, s6, 0x4000
	s_addc_u32 s7, s7, 0
	global_load_dword v31, v2, s[6:7]
	v_cmp_eq_u32_e32 vcc, 0, v250
	s_and_saveexec_b64 s[0:1], vcc
	v_mov_b32_e32 v4, 0
	v_mov_b32_e32 v5, 48
	ds_write_b32 v5, v4
	s_mov_b64 exec, s[0:1]
	s_lshl_b32 s27, s3, 10
	s_lshl_b32 s18, s2, 9
	s_add_u32 s27, s27, s18
	s_lshl_b32 s18, s27, 2
	s_add_u32 s36, s78, s18
	s_addc_u32 s37, s79, 0
	s_add_u32 s38, s80, s18
	s_addc_u32 s39, s81, 0
	s_mov_b32 s4, 30
	s_mov_b32 s5, 0
	s_mov_b32 s8, 0
	s_waitcnt vmcnt(0)
.LtkA_loop:
	s_lshl_b32 s9, 1, s4
	s_or_b32 s9, s9, s5
	s_mov_b32 s19, 0
	v_cmp_ge_u32_e64 s[10:11], v16, s9
	v_cmp_ge_u32_e64 s[12:13], v17, s9
	v_cmp_ge_u32_e64 s[14:15], v18, s9
	v_cmp_ge_u32_e64 s[16:17], v19, s9
	s_bcnt1_i32_b64 s18, s[10:11]
	s_add_u32 s19, s19, s18
	v_cmp_ge_u32_e64 s[10:11], v20, s9
	s_bcnt1_i32_b64 s18, s[12:13]
	s_add_u32 s19, s19, s18
	v_cmp_ge_u32_e64 s[12:13], v21, s9
	s_bcnt1_i32_b64 s18, s[14:15]
	s_add_u32 s19, s19, s18
	v_cmp_ge_u32_e64 s[14:15], v22, s9
	s_bcnt1_i32_b64 s18, s[16:17]
	s_add_u32 s19, s19, s18
	v_cmp_ge_u32_e64 s[16:17], v23, s9
	s_bcnt1_i32_b64 s18, s[10:11]
	s_add_u32 s19, s19, s18
	v_cmp_ge_u32_e64 s[10:11], v24, s9
	s_bcnt1_i32_b64 s18, s[12:13]
	s_add_u32 s19, s19, s18
	v_cmp_ge_u32_e64 s[12:13], v25, s9
	s_bcnt1_i32_b64 s18, s[14:15]
	s_add_u32 s19, s19, s18
	v_cmp_ge_u32_e64 s[14:15], v26, s9
	s_bcnt1_i32_b64 s18, s[16:17]
	s_add_u32 s19, s19, s18
	v_cmp_ge_u32_e64 s[16:17], v27, s9
	s_bcnt1_i32_b64 s18, s[10:11]
	s_add_u32 s19, s19, s18
	v_cmp_ge_u32_e64 s[10:11], v28, s9
	s_bcnt1_i32_b64 s18, s[12:13]
	s_add_u32 s19, s19, s18
	v_cmp_ge_u32_e64 s[12:13], v29, s9
	s_bcnt1_i32_b64 s18, s[14:15]
	s_add_u32 s19, s19, s18
	v_cmp_ge_u32_e64 s[14:15], v30, s9
	s_bcnt1_i32_b64 s18, s[16:17]
	s_add_u32 s19, s19, s18
	v_cmp_ge_u32_e64 s[16:17], v31, s9
	s_bcnt1_i32_b64 s18, s[10:11]
	s_add_u32 s19, s19, s18
	s_bcnt1_i32_b64 s18, s[12:13]
	s_add_u32 s19, s19, s18
	s_bcnt1_i32_b64 s18, s[14:15]
	s_add_u32 s19, s19, s18
	s_bcnt1_i32_b64 s18, s[16:17]
	s_add_u32 s19, s19, s18
	v_mov_b32_e32 v5, s19
	v_add_u32_e32 v4, s8, v3
	s_and_saveexec_b64 s[0:1], s[30:31]
	ds_write_b32 v4, v5
	s_mov_b64 exec, s[0:1]
	s_waitcnt lgkmcnt(0)
	s_barrier
	v_mov_b32_e32 v4, s8
	ds_read_b128 v[8:11], v4
	s_xor_b32 s8, s8, 16
	s_waitcnt lgkmcnt(0)
	v_add_u32_e32 v8, v8, v9
	v_add3_u32 v8, v8, v10, v11
	s_nop 1
	v_readfirstlane_b32 s20, v8
	s_nop 1
	s_cmp_ge_u32 s20, 0x200
	s_cselect_b32 s5, s9, s5
	s_add_i32 s4, s4, -1
	s_cmp_ge_i32 s4, 0
	s_cbranch_scc1 .LtkA_loop
	s_mov_b32 s19, 0
	v_cmp_gt_u32_e64 s[10:11], v16, s5
	v_cmp_gt_u32_e64 s[12:13], v17, s5
	v_cmp_gt_u32_e64 s[14:15], v18, s5
	v_cmp_gt_u32_e64 s[16:17], v19, s5
	v_mbcnt_lo_u32_b32 v200, s10, 0
	v_mbcnt_hi_u32_b32 v200, s11, v200
	v_add_u32_e32 v200, s19, v200
	s_bcnt1_i32_b64 s18, s[10:11]
	s_add_u32 s19, s19, s18
	v_mbcnt_lo_u32_b32 v201, s12, 0
	v_mbcnt_hi_u32_b32 v201, s13, v201
	v_add_u32_e32 v201, s19, v201
	s_bcnt1_i32_b64 s18, s[12:13]
	s_add_u32 s19, s19, s18
	v_mbcnt_lo_u32_b32 v202, s14, 0
	v_mbcnt_hi_u32_b32 v202, s15, v202
	v_add_u32_e32 v202, s19, v202
	s_bcnt1_i32_b64 s18, s[14:15]
	s_add_u32 s19, s19, s18
	v_mbcnt_lo_u32_b32 v203, s16, 0
	v_mbcnt_hi_u32_b32 v203, s17, v203
	v_add_u32_e32 v203, s19, v203
	s_bcnt1_i32_b64 s18, s[16:17]
	s_add_u32 s19, s19, s18
	s_nop 1
	v_cmp_gt_u32_e64 s[10:11], v20, s5
	v_cmp_gt_u32_e64 s[12:13], v21, s5
	v_cmp_gt_u32_e64 s[14:15], v22, s5
	v_cmp_gt_u32_e64 s[16:17], v23, s5
	v_mbcnt_lo_u32_b32 v204, s10, 0
	v_mbcnt_hi_u32_b32 v204, s11, v204
	v_add_u32_e32 v204, s19, v204
	s_bcnt1_i32_b64 s18, s[10:11]
	s_add_u32 s19, s19, s18
	v_mbcnt_lo_u32_b32 v205, s12, 0
	v_mbcnt_hi_u32_b32 v205, s13, v205
	v_add_u32_e32 v205, s19, v205
	s_bcnt1_i32_b64 s18, s[12:13]
	s_add_u32 s19, s19, s18
	v_mbcnt_lo_u32_b32 v206, s14, 0
	v_mbcnt_hi_u32_b32 v206, s15, v206
	v_add_u32_e32 v206, s19, v206
	s_bcnt1_i32_b64 s18, s[14:15]
	s_add_u32 s19, s19, s18
	v_mbcnt_lo_u32_b32 v207, s16, 0
	v_mbcnt_hi_u32_b32 v207, s17, v207
	v_add_u32_e32 v207, s19, v207
	s_bcnt1_i32_b64 s18, s[16:17]
	s_add_u32 s19, s19, s18
	s_nop 1
	v_cmp_gt_u32_e64 s[10:11], v24, s5
	v_cmp_gt_u32_e64 s[12:13], v25, s5
	v_cmp_gt_u32_e64 s[14:15], v26, s5
	v_cmp_gt_u32_e64 s[16:17], v27, s5
	v_mbcnt_lo_u32_b32 v208, s10, 0
	v_mbcnt_hi_u32_b32 v208, s11, v208
	v_add_u32_e32 v208, s19, v208
	s_bcnt1_i32_b64 s18, s[10:11]
	s_add_u32 s19, s19, s18
	v_mbcnt_lo_u32_b32 v209, s12, 0
	v_mbcnt_hi_u32_b32 v209, s13, v209
	v_add_u32_e32 v209, s19, v209
	s_bcnt1_i32_b64 s18, s[12:13]
	s_add_u32 s19, s19, s18
	v_mbcnt_lo_u32_b32 v210, s14, 0
	v_mbcnt_hi_u32_b32 v210, s15, v210
	v_add_u32_e32 v210, s19, v210
	s_bcnt1_i32_b64 s18, s[14:15]
	s_add_u32 s19, s19, s18
	v_mbcnt_lo_u32_b32 v211, s16, 0
	v_mbcnt_hi_u32_b32 v211, s17, v211
	v_add_u32_e32 v211, s19, v211
	s_bcnt1_i32_b64 s18, s[16:17]
	s_add_u32 s19, s19, s18
	s_nop 1
	v_cmp_gt_u32_e64 s[10:11], v28, s5
	v_cmp_gt_u32_e64 s[12:13], v29, s5
	v_cmp_gt_u32_e64 s[14:15], v30, s5
	v_cmp_gt_u32_e64 s[16:17], v31, s5
	v_mbcnt_lo_u32_b32 v212, s10, 0
	v_mbcnt_hi_u32_b32 v212, s11, v212
	v_add_u32_e32 v212, s19, v212
	s_bcnt1_i32_b64 s18, s[10:11]
	s_add_u32 s19, s19, s18
	v_mbcnt_lo_u32_b32 v213, s12, 0
	v_mbcnt_hi_u32_b32 v213, s13, v213
	v_add_u32_e32 v213, s19, v213
	s_bcnt1_i32_b64 s18, s[12:13]
	s_add_u32 s19, s19, s18
	v_mbcnt_lo_u32_b32 v214, s14, 0
	v_mbcnt_hi_u32_b32 v214, s15, v214
	v_add_u32_e32 v214, s19, v214
	s_bcnt1_i32_b64 s18, s[14:15]
	s_add_u32 s19, s19, s18
	v_mbcnt_lo_u32_b32 v215, s16, 0
	v_mbcnt_hi_u32_b32 v215, s17, v215
	v_add_u32_e32 v215, s19, v215
	s_bcnt1_i32_b64 s18, s[16:17]
	s_add_u32 s19, s19, s18
	s_nop 1
	v_mov_b32_e32 v5, s19
	v_add_u32_e32 v4, 32, v3
	s_and_saveexec_b64 s[0:1], s[30:31]
	ds_write_b32 v4, v5
	s_mov_b64 exec, s[0:1]
	s_waitcnt lgkmcnt(0)
	s_barrier
	v_mov_b32_e32 v4, 32
	ds_read_b128 v[8:11], v4
	s_waitcnt lgkmcnt(0)
	v_readfirstlane_b32 s20, v8
	v_readfirstlane_b32 s21, v9
	v_readfirstlane_b32 s22, v10
	v_readfirstlane_b32 s23, v11
	s_nop 3
	s_mov_b32 s24, 0
	s_cmp_gt_u32 s34, 0
	s_cselect_b32 s18, s20, 0
	s_add_u32 s24, s24, s18
	s_cmp_gt_u32 s34, 1
	s_cselect_b32 s18, s21, 0
	s_add_u32 s24, s24, s18
	s_cmp_gt_u32 s34, 2
	s_cselect_b32 s18, s22, 0
	s_add_u32 s24, s24, s18
	s_add_u32 s25, s20, s21
	s_add_u32 s25, s25, s22
	s_add_u32 s25, s25, s23
	s_sub_u32 s26, 0x200, s25
	v_cmp_lt_u32_e32 vcc, s5, v16
	s_and_saveexec_b64 s[0:1], vcc
	v_add_u32_e32 v200, s24, v200
	v_mov_b32_e32 v5, v1
	v_lshlrev_b32_e32 v4, 2, v200
	v_lshlrev_b32_e32 v7, 2, v5
	global_store_dword v4, v5, s[36:37]
	global_store_dword v4, v16, s[38:39]
	global_atomic_add v216, v7, v6, s[84:85] sc0
	s_mov_b64 exec, s[0:1]
	v_cmp_lt_u32_e32 vcc, s5, v17
	s_and_saveexec_b64 s[0:1], vcc
	v_add_u32_e32 v201, s24, v201
	v_add_u32_e32 v5, 0x100, v1
	v_lshlrev_b32_e32 v4, 2, v201
	v_lshlrev_b32_e32 v7, 2, v5
	global_store_dword v4, v5, s[36:37]
	global_store_dword v4, v17, s[38:39]
	global_atomic_add v217, v7, v6, s[84:85] sc0
	s_mov_b64 exec, s[0:1]
	v_cmp_lt_u32_e32 vcc, s5, v18
	s_and_saveexec_b64 s[0:1], vcc
	v_add_u32_e32 v202, s24, v202
	v_add_u32_e32 v5, 0x200, v1
	v_lshlrev_b32_e32 v4, 2, v202
	v_lshlrev_b32_e32 v7, 2, v5
	global_store_dword v4, v5, s[36:37]
	global_store_dword v4, v18, s[38:39]
	global_atomic_add v218, v7, v6, s[84:85] sc0
	s_mov_b64 exec, s[0:1]
	v_cmp_lt_u32_e32 vcc, s5, v19
	s_and_saveexec_b64 s[0:1], vcc
	v_add_u32_e32 v203, s24, v203
	v_add_u32_e32 v5, 0x300, v1
	v_lshlrev_b32_e32 v4, 2, v203
	v_lshlrev_b32_e32 v7, 2, v5
	global_store_dword v4, v5, s[36:37]
	global_store_dword v4, v19, s[38:39]
	global_atomic_add v219, v7, v6, s[84:85] sc0
	s_mov_b64 exec, s[0:1]
	v_cmp_lt_u32_e32 vcc, s5, v20
	s_and_saveexec_b64 s[0:1], vcc
	v_add_u32_e32 v204, s24, v204
	v_add_u32_e32 v5, 0x400, v1
	v_lshlrev_b32_e32 v4, 2, v204
	v_lshlrev_b32_e32 v7, 2, v5
	global_store_dword v4, v5, s[36:37]
	global_store_dword v4, v20, s[38:39]
	global_atomic_add v220, v7, v6, s[84:85] sc0
	s_mov_b64 exec, s[0:1]
	v_cmp_lt_u32_e32 vcc, s5, v21
	s_and_saveexec_b64 s[0:1], vcc
	v_add_u32_e32 v205, s24, v205
	v_add_u32_e32 v5, 0x500, v1
	v_lshlrev_b32_e32 v4, 2, v205
	v_lshlrev_b32_e32 v7, 2, v5
	global_store_dword v4, v5, s[36:37]
	global_store_dword v4, v21, s[38:39]
	global_atomic_add v221, v7, v6, s[84:85] sc0
	s_mov_b64 exec, s[0:1]
	v_cmp_lt_u32_e32 vcc, s5, v22
	s_and_saveexec_b64 s[0:1], vcc
	v_add_u32_e32 v206, s24, v206
	v_add_u32_e32 v5, 0x600, v1
	v_lshlrev_b32_e32 v4, 2, v206
	v_lshlrev_b32_e32 v7, 2, v5
	global_store_dword v4, v5, s[36:37]
	global_store_dword v4, v22, s[38:39]
	global_atomic_add v222, v7, v6, s[84:85] sc0
	s_mov_b64 exec, s[0:1]
	v_cmp_lt_u32_e32 vcc, s5, v23
	s_and_saveexec_b64 s[0:1], vcc
	v_add_u32_e32 v207, s24, v207
	v_add_u32_e32 v5, 0x700, v1
	v_lshlrev_b32_e32 v4, 2, v207
	v_lshlrev_b32_e32 v7, 2, v5
	global_store_dword v4, v5, s[36:37]
	global_store_dword v4, v23, s[38:39]
	global_atomic_add v223, v7, v6, s[84:85] sc0
	s_mov_b64 exec, s[0:1]
	v_cmp_lt_u32_e32 vcc, s5, v24
	s_and_saveexec_b64 s[0:1], vcc
	v_add_u32_e32 v208, s24, v208
	v_add_u32_e32 v5, 0x800, v1
	v_lshlrev_b32_e32 v4, 2, v208
	v_lshlrev_b32_e32 v7, 2, v5
	global_store_dword v4, v5, s[36:37]
	global_store_dword v4, v24, s[38:39]
	global_atomic_add v224, v7, v6, s[84:85] sc0
	s_mov_b64 exec, s[0:1]
	v_cmp_lt_u32_e32 vcc, s5, v25
	s_and_saveexec_b64 s[0:1], vcc
	v_add_u32_e32 v209, s24, v209
	v_add_u32_e32 v5, 0x900, v1
	v_lshlrev_b32_e32 v4, 2, v209
	v_lshlrev_b32_e32 v7, 2, v5
	global_store_dword v4, v5, s[36:37]
	global_store_dword v4, v25, s[38:39]
	global_atomic_add v225, v7, v6, s[84:85] sc0
	s_mov_b64 exec, s[0:1]
	v_cmp_lt_u32_e32 vcc, s5, v26
	s_and_saveexec_b64 s[0:1], vcc
	v_add_u32_e32 v210, s24, v210
	v_add_u32_e32 v5, 0xa00, v1
	v_lshlrev_b32_e32 v4, 2, v210
	v_lshlrev_b32_e32 v7, 2, v5
	global_store_dword v4, v5, s[36:37]
	global_store_dword v4, v26, s[38:39]
	global_atomic_add v226, v7, v6, s[84:85] sc0
	s_mov_b64 exec, s[0:1]
	v_cmp_lt_u32_e32 vcc, s5, v27
	s_and_saveexec_b64 s[0:1], vcc
	v_add_u32_e32 v211, s24, v211
	v_add_u32_e32 v5, 0xb00, v1
	v_lshlrev_b32_e32 v4, 2, v211
	v_lshlrev_b32_e32 v7, 2, v5
	global_store_dword v4, v5, s[36:37]
	global_store_dword v4, v27, s[38:39]
	global_atomic_add v227, v7, v6, s[84:85] sc0
	s_mov_b64 exec, s[0:1]
	v_cmp_lt_u32_e32 vcc, s5, v28
	s_and_saveexec_b64 s[0:1], vcc
	v_add_u32_e32 v212, s24, v212
	v_add_u32_e32 v5, 0xc00, v1
	v_lshlrev_b32_e32 v4, 2, v212
	v_lshlrev_b32_e32 v7, 2, v5
	global_store_dword v4, v5, s[36:37]
	global_store_dword v4, v28, s[38:39]
	global_atomic_add v228, v7, v6, s[84:85] sc0
	s_mov_b64 exec, s[0:1]
	v_cmp_lt_u32_e32 vcc, s5, v29
	s_and_saveexec_b64 s[0:1], vcc
	v_add_u32_e32 v213, s24, v213
	v_add_u32_e32 v5, 0xd00, v1
	v_lshlrev_b32_e32 v4, 2, v213
	v_lshlrev_b32_e32 v7, 2, v5
	global_store_dword v4, v5, s[36:37]
	global_store_dword v4, v29, s[38:39]
	global_atomic_add v229, v7, v6, s[84:85] sc0
	s_mov_b64 exec, s[0:1]
	v_cmp_lt_u32_e32 vcc, s5, v30
	s_and_saveexec_b64 s[0:1], vcc
	v_add_u32_e32 v214, s24, v214
	v_add_u32_e32 v5, 0xe00, v1
	v_lshlrev_b32_e32 v4, 2, v214
	v_lshlrev_b32_e32 v7, 2, v5
	global_store_dword v4, v5, s[36:37]
	global_store_dword v4, v30, s[38:39]
	global_atomic_add v230, v7, v6, s[84:85] sc0
	s_mov_b64 exec, s[0:1]
	v_cmp_lt_u32_e32 vcc, s5, v31
	s_and_saveexec_b64 s[0:1], vcc
	v_add_u32_e32 v215, s24, v215
	v_add_u32_e32 v5, 0xf00, v1
	v_lshlrev_b32_e32 v4, 2, v215
	v_lshlrev_b32_e32 v7, 2, v5
	global_store_dword v4, v5, s[36:37]
	global_store_dword v4, v31, s[38:39]
	global_atomic_add v231, v7, v6, s[84:85] sc0
	s_mov_b64 exec, s[0:1]
	s_waitcnt vmcnt(0)
	v_cmp_lt_u32_e32 vcc, s5, v16
	s_and_saveexec_b64 s[0:1], vcc
	v_mov_b32_e32 v5, v1
	v_lshl_add_u32 v4, v5, 4, v216
	v_add_u32_e32 v7, s27, v200
	v_lshlrev_b32_e32 v4, 2, v4
	global_store_dword v4, v7, s[86:87]
	s_mov_b64 exec, s[0:1]
	v_cmp_lt_u32_e32 vcc, s5, v17
	s_and_saveexec_b64 s[0:1], vcc
	v_add_u32_e32 v5, 0x100, v1
	v_lshl_add_u32 v4, v5, 4, v217
	v_add_u32_e32 v7, s27, v201
	v_lshlrev_b32_e32 v4, 2, v4
	global_store_dword v4, v7, s[86:87]
	s_mov_b64 exec, s[0:1]
	v_cmp_lt_u32_e32 vcc, s5, v18
	s_and_saveexec_b64 s[0:1], vcc
	v_add_u32_e32 v5, 0x200, v1
	v_lshl_add_u32 v4, v5, 4, v218
	v_add_u32_e32 v7, s27, v202
	v_lshlrev_b32_e32 v4, 2, v4
	global_store_dword v4, v7, s[86:87]
	s_mov_b64 exec, s[0:1]
	v_cmp_lt_u32_e32 vcc, s5, v19
	s_and_saveexec_b64 s[0:1], vcc
	v_add_u32_e32 v5, 0x300, v1
	v_lshl_add_u32 v4, v5, 4, v219
	v_add_u32_e32 v7, s27, v203
	v_lshlrev_b32_e32 v4, 2, v4
	global_store_dword v4, v7, s[86:87]
	s_mov_b64 exec, s[0:1]
	v_cmp_lt_u32_e32 vcc, s5, v20
	s_and_saveexec_b64 s[0:1], vcc
	v_add_u32_e32 v5, 0x400, v1
	v_lshl_add_u32 v4, v5, 4, v220
	v_add_u32_e32 v7, s27, v204
	v_lshlrev_b32_e32 v4, 2, v4
	global_store_dword v4, v7, s[86:87]
	s_mov_b64 exec, s[0:1]
	v_cmp_lt_u32_e32 vcc, s5, v21
	s_and_saveexec_b64 s[0:1], vcc
	v_add_u32_e32 v5, 0x500, v1
	v_lshl_add_u32 v4, v5, 4, v221
	v_add_u32_e32 v7, s27, v205
	v_lshlrev_b32_e32 v4, 2, v4
	global_store_dword v4, v7, s[86:87]
	s_mov_b64 exec, s[0:1]
	v_cmp_lt_u32_e32 vcc, s5, v22
	s_and_saveexec_b64 s[0:1], vcc
	v_add_u32_e32 v5, 0x600, v1
	v_lshl_add_u32 v4, v5, 4, v222
	v_add_u32_e32 v7, s27, v206
	v_lshlrev_b32_e32 v4, 2, v4
	global_store_dword v4, v7, s[86:87]
	s_mov_b64 exec, s[0:1]
	v_cmp_lt_u32_e32 vcc, s5, v23
	s_and_saveexec_b64 s[0:1], vcc
	v_add_u32_e32 v5, 0x700, v1
	v_lshl_add_u32 v4, v5, 4, v223
	v_add_u32_e32 v7, s27, v207
	v_lshlrev_b32_e32 v4, 2, v4
	global_store_dword v4, v7, s[86:87]
	s_mov_b64 exec, s[0:1]
	v_cmp_lt_u32_e32 vcc, s5, v24
	s_and_saveexec_b64 s[0:1], vcc
	v_add_u32_e32 v5, 0x800, v1
	v_lshl_add_u32 v4, v5, 4, v224
	v_add_u32_e32 v7, s27, v208
	v_lshlrev_b32_e32 v4, 2, v4
	global_store_dword v4, v7, s[86:87]
	s_mov_b64 exec, s[0:1]
	v_cmp_lt_u32_e32 vcc, s5, v25
	s_and_saveexec_b64 s[0:1], vcc
	v_add_u32_e32 v5, 0x900, v1
	v_lshl_add_u32 v4, v5, 4, v225
	v_add_u32_e32 v7, s27, v209
	v_lshlrev_b32_e32 v4, 2, v4
	global_store_dword v4, v7, s[86:87]
	s_mov_b64 exec, s[0:1]
	v_cmp_lt_u32_e32 vcc, s5, v26
	s_and_saveexec_b64 s[0:1], vcc
	v_add_u32_e32 v5, 0xa00, v1
	v_lshl_add_u32 v4, v5, 4, v226
	v_add_u32_e32 v7, s27, v210
	v_lshlrev_b32_e32 v4, 2, v4
	global_store_dword v4, v7, s[86:87]
	s_mov_b64 exec, s[0:1]
	v_cmp_lt_u32_e32 vcc, s5, v27
	s_and_saveexec_b64 s[0:1], vcc
	v_add_u32_e32 v5, 0xb00, v1
	v_lshl_add_u32 v4, v5, 4, v227
	v_add_u32_e32 v7, s27, v211
	v_lshlrev_b32_e32 v4, 2, v4
	global_store_dword v4, v7, s[86:87]
	s_mov_b64 exec, s[0:1]
	v_cmp_lt_u32_e32 vcc, s5, v28
	s_and_saveexec_b64 s[0:1], vcc
	v_add_u32_e32 v5, 0xc00, v1
	v_lshl_add_u32 v4, v5, 4, v228
	v_add_u32_e32 v7, s27, v212
	v_lshlrev_b32_e32 v4, 2, v4
	global_store_dword v4, v7, s[86:87]
	s_mov_b64 exec, s[0:1]
	v_cmp_lt_u32_e32 vcc, s5, v29
	s_and_saveexec_b64 s[0:1], vcc
	v_add_u32_e32 v5, 0xd00, v1
	v_lshl_add_u32 v4, v5, 4, v229
	v_add_u32_e32 v7, s27, v213
	v_lshlrev_b32_e32 v4, 2, v4
	global_store_dword v4, v7, s[86:87]
	s_mov_b64 exec, s[0:1]
	v_cmp_lt_u32_e32 vcc, s5, v30
	s_and_saveexec_b64 s[0:1], vcc
	v_add_u32_e32 v5, 0xe00, v1
	v_lshl_add_u32 v4, v5, 4, v230
	v_add_u32_e32 v7, s27, v214
	v_lshlrev_b32_e32 v4, 2, v4
	global_store_dword v4, v7, s[86:87]
	s_mov_b64 exec, s[0:1]
	v_cmp_lt_u32_e32 vcc, s5, v31
	s_and_saveexec_b64 s[0:1], vcc
	v_add_u32_e32 v5, 0xf00, v1
	v_lshl_add_u32 v4, v5, 4, v231
	v_add_u32_e32 v7, s27, v215
	v_lshlrev_b32_e32 v4, 2, v4
	global_store_dword v4, v7, s[86:87]
	s_mov_b64 exec, s[0:1]
	v_cmp_eq_u32_e32 vcc, s5, v16
	s_cbranch_vccz .LtkA_eq0
	s_and_saveexec_b64 s[0:1], vcc
	v_mov_b32_e32 v4, 48
	ds_add_rtn_u32 v9, v4, v6
	s_waitcnt lgkmcnt(0)
	v_cmp_gt_i32_e32 vcc, s26, v9
	s_and_b64 exec, exec, vcc
	v_add_u32_e32 v10, s25, v9
	v_lshlrev_b32_e32 v11, 2, v10
	v_mov_b32_e32 v5, v1
	global_store_dword v11, v5, s[36:37]
	global_store_dword v11, v16, s[38:39]
	v_lshlrev_b32_e32 v7, 2, v5
	global_atomic_add v12, v7, v6, s[84:85] sc0
	s_waitcnt vmcnt(0)
	v_lshl_add_u32 v13, v5, 4, v12
	v_add_u32_e32 v14, s27, v10
	v_lshlrev_b32_e32 v13, 2, v13
	global_store_dword v13, v14, s[86:87]
	s_mov_b64 exec, s[0:1]
.LtkA_eq0:
	v_cmp_eq_u32_e32 vcc, s5, v17
	s_cbranch_vccz .LtkA_eq1
	s_and_saveexec_b64 s[0:1], vcc
	v_mov_b32_e32 v4, 48
	ds_add_rtn_u32 v9, v4, v6
	s_waitcnt lgkmcnt(0)
	v_cmp_gt_i32_e32 vcc, s26, v9
	s_and_b64 exec, exec, vcc
	v_add_u32_e32 v10, s25, v9
	v_lshlrev_b32_e32 v11, 2, v10
	v_add_u32_e32 v5, 0x100, v1
	global_store_dword v11, v5, s[36:37]
	global_store_dword v11, v17, s[38:39]
	v_lshlrev_b32_e32 v7, 2, v5
	global_atomic_add v12, v7, v6, s[84:85] sc0
	s_waitcnt vmcnt(0)
	v_lshl_add_u32 v13, v5, 4, v12
	v_add_u32_e32 v14, s27, v10
	v_lshlrev_b32_e32 v13, 2, v13
	global_store_dword v13, v14, s[86:87]
	s_mov_b64 exec, s[0:1]
.LtkA_eq1:
	v_cmp_eq_u32_e32 vcc, s5, v18
	s_cbranch_vccz .LtkA_eq2
	s_and_saveexec_b64 s[0:1], vcc
	v_mov_b32_e32 v4, 48
	ds_add_rtn_u32 v9, v4, v6
	s_waitcnt lgkmcnt(0)
	v_cmp_gt_i32_e32 vcc, s26, v9
	s_and_b64 exec, exec, vcc
	v_add_u32_e32 v10, s25, v9
	v_lshlrev_b32_e32 v11, 2, v10
	v_add_u32_e32 v5, 0x200, v1
	global_store_dword v11, v5, s[36:37]
	global_store_dword v11, v18, s[38:39]
	v_lshlrev_b32_e32 v7, 2, v5
	global_atomic_add v12, v7, v6, s[84:85] sc0
	s_waitcnt vmcnt(0)
	v_lshl_add_u32 v13, v5, 4, v12
	v_add_u32_e32 v14, s27, v10
	v_lshlrev_b32_e32 v13, 2, v13
	global_store_dword v13, v14, s[86:87]
	s_mov_b64 exec, s[0:1]
.LtkA_eq2:
	v_cmp_eq_u32_e32 vcc, s5, v19
	s_cbranch_vccz .LtkA_eq3
	s_and_saveexec_b64 s[0:1], vcc
	v_mov_b32_e32 v4, 48
	ds_add_rtn_u32 v9, v4, v6
	s_waitcnt lgkmcnt(0)
	v_cmp_gt_i32_e32 vcc, s26, v9
	s_and_b64 exec, exec, vcc
	v_add_u32_e32 v10, s25, v9
	v_lshlrev_b32_e32 v11, 2, v10
	v_add_u32_e32 v5, 0x300, v1
	global_store_dword v11, v5, s[36:37]
	global_store_dword v11, v19, s[38:39]
	v_lshlrev_b32_e32 v7, 2, v5
	global_atomic_add v12, v7, v6, s[84:85] sc0
	s_waitcnt vmcnt(0)
	v_lshl_add_u32 v13, v5, 4, v12
	v_add_u32_e32 v14, s27, v10
	v_lshlrev_b32_e32 v13, 2, v13
	global_store_dword v13, v14, s[86:87]
	s_mov_b64 exec, s[0:1]
.LtkA_eq3:
	v_cmp_eq_u32_e32 vcc, s5, v20
	s_cbranch_vccz .LtkA_eq4
	s_and_saveexec_b64 s[0:1], vcc
	v_mov_b32_e32 v4, 48
	ds_add_rtn_u32 v9, v4, v6
	s_waitcnt lgkmcnt(0)
	v_cmp_gt_i32_e32 vcc, s26, v9
	s_and_b64 exec, exec, vcc
	v_add_u32_e32 v10, s25, v9
	v_lshlrev_b32_e32 v11, 2, v10
	v_add_u32_e32 v5, 0x400, v1
	global_store_dword v11, v5, s[36:37]
	global_store_dword v11, v20, s[38:39]
	v_lshlrev_b32_e32 v7, 2, v5
	global_atomic_add v12, v7, v6, s[84:85] sc0
	s_waitcnt vmcnt(0)
	v_lshl_add_u32 v13, v5, 4, v12
	v_add_u32_e32 v14, s27, v10
	v_lshlrev_b32_e32 v13, 2, v13
	global_store_dword v13, v14, s[86:87]
	s_mov_b64 exec, s[0:1]
.LtkA_eq4:
	v_cmp_eq_u32_e32 vcc, s5, v21
	s_cbranch_vccz .LtkA_eq5
	s_and_saveexec_b64 s[0:1], vcc
	v_mov_b32_e32 v4, 48
	ds_add_rtn_u32 v9, v4, v6
	s_waitcnt lgkmcnt(0)
	v_cmp_gt_i32_e32 vcc, s26, v9
	s_and_b64 exec, exec, vcc
	v_add_u32_e32 v10, s25, v9
	v_lshlrev_b32_e32 v11, 2, v10
	v_add_u32_e32 v5, 0x500, v1
	global_store_dword v11, v5, s[36:37]
	global_store_dword v11, v21, s[38:39]
	v_lshlrev_b32_e32 v7, 2, v5
	global_atomic_add v12, v7, v6, s[84:85] sc0
	s_waitcnt vmcnt(0)
	v_lshl_add_u32 v13, v5, 4, v12
	v_add_u32_e32 v14, s27, v10
	v_lshlrev_b32_e32 v13, 2, v13
	global_store_dword v13, v14, s[86:87]
	s_mov_b64 exec, s[0:1]
.LtkA_eq5:
	v_cmp_eq_u32_e32 vcc, s5, v22
	s_cbranch_vccz .LtkA_eq6
	s_and_saveexec_b64 s[0:1], vcc
	v_mov_b32_e32 v4, 48
	ds_add_rtn_u32 v9, v4, v6
	s_waitcnt lgkmcnt(0)
	v_cmp_gt_i32_e32 vcc, s26, v9
	s_and_b64 exec, exec, vcc
	v_add_u32_e32 v10, s25, v9
	v_lshlrev_b32_e32 v11, 2, v10
	v_add_u32_e32 v5, 0x600, v1
	global_store_dword v11, v5, s[36:37]
	global_store_dword v11, v22, s[38:39]
	v_lshlrev_b32_e32 v7, 2, v5
	global_atomic_add v12, v7, v6, s[84:85] sc0
	s_waitcnt vmcnt(0)
	v_lshl_add_u32 v13, v5, 4, v12
	v_add_u32_e32 v14, s27, v10
	v_lshlrev_b32_e32 v13, 2, v13
	global_store_dword v13, v14, s[86:87]
	s_mov_b64 exec, s[0:1]
.LtkA_eq6:
	v_cmp_eq_u32_e32 vcc, s5, v23
	s_cbranch_vccz .LtkA_eq7
	s_and_saveexec_b64 s[0:1], vcc
	v_mov_b32_e32 v4, 48
	ds_add_rtn_u32 v9, v4, v6
	s_waitcnt lgkmcnt(0)
	v_cmp_gt_i32_e32 vcc, s26, v9
	s_and_b64 exec, exec, vcc
	v_add_u32_e32 v10, s25, v9
	v_lshlrev_b32_e32 v11, 2, v10
	v_add_u32_e32 v5, 0x700, v1
	global_store_dword v11, v5, s[36:37]
	global_store_dword v11, v23, s[38:39]
	v_lshlrev_b32_e32 v7, 2, v5
	global_atomic_add v12, v7, v6, s[84:85] sc0
	s_waitcnt vmcnt(0)
	v_lshl_add_u32 v13, v5, 4, v12
	v_add_u32_e32 v14, s27, v10
	v_lshlrev_b32_e32 v13, 2, v13
	global_store_dword v13, v14, s[86:87]
	s_mov_b64 exec, s[0:1]
.LtkA_eq7:
	v_cmp_eq_u32_e32 vcc, s5, v24
	s_cbranch_vccz .LtkA_eq8
	s_and_saveexec_b64 s[0:1], vcc
	v_mov_b32_e32 v4, 48
	ds_add_rtn_u32 v9, v4, v6
	s_waitcnt lgkmcnt(0)
	v_cmp_gt_i32_e32 vcc, s26, v9
	s_and_b64 exec, exec, vcc
	v_add_u32_e32 v10, s25, v9
	v_lshlrev_b32_e32 v11, 2, v10
	v_add_u32_e32 v5, 0x800, v1
	global_store_dword v11, v5, s[36:37]
	global_store_dword v11, v24, s[38:39]
	v_lshlrev_b32_e32 v7, 2, v5
	global_atomic_add v12, v7, v6, s[84:85] sc0
	s_waitcnt vmcnt(0)
	v_lshl_add_u32 v13, v5, 4, v12
	v_add_u32_e32 v14, s27, v10
	v_lshlrev_b32_e32 v13, 2, v13
	global_store_dword v13, v14, s[86:87]
	s_mov_b64 exec, s[0:1]
.LtkA_eq8:
	v_cmp_eq_u32_e32 vcc, s5, v25
	s_cbranch_vccz .LtkA_eq9
	s_and_saveexec_b64 s[0:1], vcc
	v_mov_b32_e32 v4, 48
	ds_add_rtn_u32 v9, v4, v6
	s_waitcnt lgkmcnt(0)
	v_cmp_gt_i32_e32 vcc, s26, v9
	s_and_b64 exec, exec, vcc
	v_add_u32_e32 v10, s25, v9
	v_lshlrev_b32_e32 v11, 2, v10
	v_add_u32_e32 v5, 0x900, v1
	global_store_dword v11, v5, s[36:37]
	global_store_dword v11, v25, s[38:39]
	v_lshlrev_b32_e32 v7, 2, v5
	global_atomic_add v12, v7, v6, s[84:85] sc0
	s_waitcnt vmcnt(0)
	v_lshl_add_u32 v13, v5, 4, v12
	v_add_u32_e32 v14, s27, v10
	v_lshlrev_b32_e32 v13, 2, v13
	global_store_dword v13, v14, s[86:87]
	s_mov_b64 exec, s[0:1]
.LtkA_eq9:
	v_cmp_eq_u32_e32 vcc, s5, v26
	s_cbranch_vccz .LtkA_eq10
	s_and_saveexec_b64 s[0:1], vcc
	v_mov_b32_e32 v4, 48
	ds_add_rtn_u32 v9, v4, v6
	s_waitcnt lgkmcnt(0)
	v_cmp_gt_i32_e32 vcc, s26, v9
	s_and_b64 exec, exec, vcc
	v_add_u32_e32 v10, s25, v9
	v_lshlrev_b32_e32 v11, 2, v10
	v_add_u32_e32 v5, 0xa00, v1
	global_store_dword v11, v5, s[36:37]
	global_store_dword v11, v26, s[38:39]
	v_lshlrev_b32_e32 v7, 2, v5
	global_atomic_add v12, v7, v6, s[84:85] sc0
	s_waitcnt vmcnt(0)
	v_lshl_add_u32 v13, v5, 4, v12
	v_add_u32_e32 v14, s27, v10
	v_lshlrev_b32_e32 v13, 2, v13
	global_store_dword v13, v14, s[86:87]
	s_mov_b64 exec, s[0:1]
.LtkA_eq10:
	v_cmp_eq_u32_e32 vcc, s5, v27
	s_cbranch_vccz .LtkA_eq11
	s_and_saveexec_b64 s[0:1], vcc
	v_mov_b32_e32 v4, 48
	ds_add_rtn_u32 v9, v4, v6
	s_waitcnt lgkmcnt(0)
	v_cmp_gt_i32_e32 vcc, s26, v9
	s_and_b64 exec, exec, vcc
	v_add_u32_e32 v10, s25, v9
	v_lshlrev_b32_e32 v11, 2, v10
	v_add_u32_e32 v5, 0xb00, v1
	global_store_dword v11, v5, s[36:37]
	global_store_dword v11, v27, s[38:39]
	v_lshlrev_b32_e32 v7, 2, v5
	global_atomic_add v12, v7, v6, s[84:85] sc0
	s_waitcnt vmcnt(0)
	v_lshl_add_u32 v13, v5, 4, v12
	v_add_u32_e32 v14, s27, v10
	v_lshlrev_b32_e32 v13, 2, v13
	global_store_dword v13, v14, s[86:87]
	s_mov_b64 exec, s[0:1]
.LtkA_eq11:
	v_cmp_eq_u32_e32 vcc, s5, v28
	s_cbranch_vccz .LtkA_eq12
	s_and_saveexec_b64 s[0:1], vcc
	v_mov_b32_e32 v4, 48
	ds_add_rtn_u32 v9, v4, v6
	s_waitcnt lgkmcnt(0)
	v_cmp_gt_i32_e32 vcc, s26, v9
	s_and_b64 exec, exec, vcc
	v_add_u32_e32 v10, s25, v9
	v_lshlrev_b32_e32 v11, 2, v10
	v_add_u32_e32 v5, 0xc00, v1
	global_store_dword v11, v5, s[36:37]
	global_store_dword v11, v28, s[38:39]
	v_lshlrev_b32_e32 v7, 2, v5
	global_atomic_add v12, v7, v6, s[84:85] sc0
	s_waitcnt vmcnt(0)
	v_lshl_add_u32 v13, v5, 4, v12
	v_add_u32_e32 v14, s27, v10
	v_lshlrev_b32_e32 v13, 2, v13
	global_store_dword v13, v14, s[86:87]
	s_mov_b64 exec, s[0:1]
.LtkA_eq12:
	v_cmp_eq_u32_e32 vcc, s5, v29
	s_cbranch_vccz .LtkA_eq13
	s_and_saveexec_b64 s[0:1], vcc
	v_mov_b32_e32 v4, 48
	ds_add_rtn_u32 v9, v4, v6
	s_waitcnt lgkmcnt(0)
	v_cmp_gt_i32_e32 vcc, s26, v9
	s_and_b64 exec, exec, vcc
	v_add_u32_e32 v10, s25, v9
	v_lshlrev_b32_e32 v11, 2, v10
	v_add_u32_e32 v5, 0xd00, v1
	global_store_dword v11, v5, s[36:37]
	global_store_dword v11, v29, s[38:39]
	v_lshlrev_b32_e32 v7, 2, v5
	global_atomic_add v12, v7, v6, s[84:85] sc0
	s_waitcnt vmcnt(0)
	v_lshl_add_u32 v13, v5, 4, v12
	v_add_u32_e32 v14, s27, v10
	v_lshlrev_b32_e32 v13, 2, v13
	global_store_dword v13, v14, s[86:87]
	s_mov_b64 exec, s[0:1]
.LtkA_eq13:
	v_cmp_eq_u32_e32 vcc, s5, v30
	s_cbranch_vccz .LtkA_eq14
	s_and_saveexec_b64 s[0:1], vcc
	v_mov_b32_e32 v4, 48
	ds_add_rtn_u32 v9, v4, v6
	s_waitcnt lgkmcnt(0)
	v_cmp_gt_i32_e32 vcc, s26, v9
	s_and_b64 exec, exec, vcc
	v_add_u32_e32 v10, s25, v9
	v_lshlrev_b32_e32 v11, 2, v10
	v_add_u32_e32 v5, 0xe00, v1
	global_store_dword v11, v5, s[36:37]
	global_store_dword v11, v30, s[38:39]
	v_lshlrev_b32_e32 v7, 2, v5
	global_atomic_add v12, v7, v6, s[84:85] sc0
	s_waitcnt vmcnt(0)
	v_lshl_add_u32 v13, v5, 4, v12
	v_add_u32_e32 v14, s27, v10
	v_lshlrev_b32_e32 v13, 2, v13
	global_store_dword v13, v14, s[86:87]
	s_mov_b64 exec, s[0:1]
.LtkA_eq14:
	v_cmp_eq_u32_e32 vcc, s5, v31
	s_cbranch_vccz .LtkA_eq15
	s_and_saveexec_b64 s[0:1], vcc
	v_mov_b32_e32 v4, 48
	ds_add_rtn_u32 v9, v4, v6
	s_waitcnt lgkmcnt(0)
	v_cmp_gt_i32_e32 vcc, s26, v9
	s_and_b64 exec, exec, vcc
	v_add_u32_e32 v10, s25, v9
	v_lshlrev_b32_e32 v11, 2, v10
	v_add_u32_e32 v5, 0xf00, v1
	global_store_dword v11, v5, s[36:37]
	global_store_dword v11, v31, s[38:39]
	v_lshlrev_b32_e32 v7, 2, v5
	global_atomic_add v12, v7, v6, s[84:85] sc0
	s_waitcnt vmcnt(0)
	v_lshl_add_u32 v13, v5, 4, v12
	v_add_u32_e32 v14, s27, v10
	v_lshlrev_b32_e32 v13, 2, v13
	global_store_dword v13, v14, s[86:87]
	s_mov_b64 exec, s[0:1]
.LtkA_eq15:
	s_add_i32 s33, s33, s92
	s_cmp_lt_i32 s33, 32
	s_barrier
	s_cbranch_scc1 .LtkA_item

.LBB0_1927:
	s_or_b64 exec, exec, s[0:1]
	v_readlane_b32 s0, v254, 2
	v_readlane_b32 s1, v254, 3
	s_andn2_b64 vcc, exec, s[0:1]
	v_readlane_b32 s0, v253, 4
	s_waitcnt lgkmcnt(0)
	s_barrier
	v_readlane_b32 s1, v253, 5
	s_cbranch_vccnz .LBB0_2162
	s_waitcnt vmcnt(0)
	v_readlane_b32 s0, v253, 4
	v_readlane_b32 s1, v253, 5
	v_lshrrev_b32_e32 v0, 6, v250
	s_sub_u32 s0, s0, 0x228
	s_subb_u32 s1, s1, 0
	s_load_dwordx4 s[76:79], s[0:1], 0x1a8
	s_load_dwordx2 s[80:81], s[0:1], 0x1b8
	s_load_dwordx4 s[84:87], s[0:1], 0x1d8
	v_readfirstlane_b32 s34, v0
	v_lshlrev_b32_e32 v3, 2, v0
	v_and_b32_e32 v4, 63, v250
	v_mov_b32_e32 v6, 1
	v_cmp_eq_u32_e64 s[30:31], 0, v4
	s_mov_b32 s33, s97
	s_waitcnt lgkmcnt(0)
